# pass C epilogue: all eight head-norm gain loads issued before the first output group (were serialized behind each group's store)
# baseline (speedup 1.0000x reference)
; #define LAS __attribute__((address_space(3)))
; __device__ __forceinline__ void gla_passC(LAS unsigned char* lds, int uidx, const bf16_t* PR, const bf16_t* SUB, const bf16_t* QT, const bf16_t* AM, const float* gn  ,
;                                           bf16_t* Y, int tid, int wid, int lane) {
;     const int b = uidx >> 7, c = (uidx >> 2) & 31, h = uidx & 3; const int tok0 = b * SEQ + c * 64; const int bh = b * 4 + h;
;     LAS bf16_t* Qs = (LAS bf16_t*)lds;
;     LAS bf16_t* As = (LAS bf16_t*)(lds + 17408);
;     LAS bf16_t* Vn = (LAS bf16_t*)(lds + 26624);
;     LAS bf16_t* Sn = (LAS bf16_t*)(lds + 61440);
;     LAS float* Of = (LAS float*)(lds + 61440);
;     const int r = lane & 15, q = lane >> 4;
;     u32x4 ogr[4];
;     { const bf16_t* gp0 = PR + (size_t)(tok0 + (tid >> 3)) * PRW + 3072 + h * DV + (tid & 7) * 32;
; #pragma unroll
;       for (int j = 0; j < 4; ++j) ogr[j] = *(const u32x4*)(gp0 + 8 * j); }
;     { const bf16_t* sp = SUB + ((size_t)bh * NCH + c) * (DK * DV);
; #pragma unroll
;       for (int i = 0; i < 8; ++i) { const int id = tid + 512 * i, k = id >> 5, cc = id & 31; *(LAS u32x4*)(Sn + k * 272 + cc * 8) = *(const u32x4*)(sp + k * DV + cc * 8); } }
; #pragma unroll
;     for (int i = 0; i < 2; ++i) { const int id = tid + 512 * i, row = id >> 4, cc = id & 15; *(LAS u32x4*)(Qs + row * 136 + cc * 8) = *(const u32x4*)(QT + (size_t)(tok0 + row) * QKD + h * DK + cc * 8); }
;     { const int row = tid >> 3, cc = tid & 7; *(LAS u32x4*)(As + row * 72 + cc * 8) = *(const u32x4*)(AM + (size_t)uidx * 4096 + row * 64 + cc * 8); }
;     stage_v(Vn, PR, tok0, h, tid);
;     __syncthreads();
.LBB0_487:
	s_ashr_i32 s10, s6, 7
	s_bfe_u32 s25, s6, 0x50002
	s_lshl_b32 s22, s10, 11
	s_lshl_b32 s23, s25, 6
	s_and_b32 s7, s6, 3
	s_or_b32 s24, s23, s22
	s_lshl_b32 s10, s10, 2
	s_or_b32 s26, s10, s7
	v_add_u32_e32 v74, s24, v78
	v_ashrrev_i32_e32 v75, 31, v74
	s_ashr_i32 s27, s26, 31
	v_lshlrev_b64 v[0:1], 13, v[74:75]
	s_lshl_b32 s10, s7, 8
	s_lshl_b32 s22, s7, 9
	s_lshl_b64 s[26:27], s[26:27], 21
	v_lshl_add_u64 v[0:1], s[4:5], 0, v[0:1]
	s_mov_b32 s23, s11
	s_add_u32 s26, s8, s26
	v_lshl_add_u64 v[0:1], v[0:1], 0, s[22:23]
	s_addc_u32 s27, s9, s27
	s_lshl_b32 s25, s25, 16
	v_lshl_add_u64 v[0:1], v[0:1], 0, v[168:169]
	s_mov_b64 s[28:29], 0x1800
	s_add_u32 s26, s26, s25
	v_lshl_add_u64 v[8:9], v[0:1], 0, s[28:29]
	v_add_co_u32_e32 v0, vcc, s15, v0
	s_addc_u32 s27, s27, 0
	v_mov_b32_e32 v71, v169
	v_addc_co_u32_e32 v1, vcc, 0, v1, vcc
	v_lshl_add_u64 v[12:13], s[26:27], 0, v[70:71]
	global_load_dwordx4 v[36:39], v[0:1], off offset:2048
	s_nop 0
	global_load_dwordx4 v[0:3], v[8:9], off offset:48
	global_load_dwordx4 v[4:7], v[8:9], off offset:32
	global_load_dwordx4 v[20:23], v[8:9], off offset:16
	v_lshl_add_u64 v[8:9], v[48:49], 1, v[12:13]
	global_load_dwordx4 v[128:131], v[8:9], off
	v_lshlrev_b64 v[74:75], 12, v[74:75]
	v_lshl_add_u64 v[74:75], s[2:3], 0, v[74:75]
	v_lshl_add_u64 v[74:75], v[74:75], 0, s[22:23]
	s_add_i32 s6, s6, s82
	v_lshl_add_u64 v[8:9], v[50:51], 1, v[12:13]
	global_load_dwordx4 v[132:135], v[8:9], off
	v_lshl_add_u64 v[8:9], v[52:53], 1, v[12:13]
	global_load_dwordx4 v[136:139], v[8:9], off
	v_lshl_add_u64 v[8:9], v[54:55], 1, v[12:13]
	global_load_dwordx4 v[140:143], v[8:9], off
	v_lshl_add_u64 v[8:9], v[56:57], 1, v[12:13]
	global_load_dwordx4 v[144:147], v[8:9], off
	v_lshl_add_u64 v[8:9], v[58:59], 1, v[12:13]
	global_load_dwordx4 v[148:151], v[8:9], off
	v_lshl_add_u64 v[8:9], v[60:61], 1, v[12:13]
	global_load_dwordx4 v[152:155], v[8:9], off
	v_lshl_add_u64 v[8:9], v[62:63], 1, v[12:13]
	global_load_dwordx4 v[156:159], v[8:9], off
	v_lshl_add_u64 v[12:13], v[64:65], 0, s[10:11]
	s_lshl_b32 s10, s7, 10
	s_mov_b32 s7, 0x18c84000
	s_cmpk_gt_i32 s6, 0x1ff
	v_add_u32_e32 v8, s24, v83
	v_ashrrev_i32_e32 v9, 31, v8
	v_lshlrev_b64 v[8:9], 10, v[8:9]
	v_lshl_add_u64 v[8:9], v[12:13], 0, v[8:9]
	global_load_dwordx4 v[160:163], v[8:9], off
	v_add_u32_e32 v8, s24, v84
	v_ashrrev_i32_e32 v9, 31, v8
	v_lshlrev_b64 v[8:9], 10, v[8:9]
	v_lshl_add_u64 v[8:9], v[12:13], 0, v[8:9]
	global_load_dwordx4 v[164:167], v[8:9], off
	global_load_dwordx4 v[178:181], v[68:69], off
	v_lshl_add_u64 v[68:69], v[68:69], 0, s[34:35]
	v_add_u32_e32 v8, s24, v79
	v_ashrrev_i32_e32 v9, 31, v8
	v_lshlrev_b64 v[8:9], 13, v[8:9]
	v_lshl_add_u64 v[8:9], s[4:5], 0, v[8:9]
	v_lshl_add_u64 v[8:9], v[8:9], 0, s[22:23]
	v_lshl_add_u64 v[8:9], v[8:9], 0, v[70:71]
	v_add_co_u32_e32 v8, vcc, s15, v8
	s_nop 1
	v_addc_co_u32_e32 v9, vcc, 0, v9, vcc
	global_load_dwordx4 v[182:185], v[8:9], off
	v_add_u32_e32 v8, s24, v80
	v_ashrrev_i32_e32 v9, 31, v8
	v_lshlrev_b64 v[8:9], 13, v[8:9]
	v_lshl_add_u64 v[8:9], s[4:5], 0, v[8:9]
	v_lshl_add_u64 v[8:9], v[8:9], 0, s[22:23]
	v_lshl_add_u64 v[8:9], v[8:9], 0, v[70:71]
	v_add_co_u32_e32 v8, vcc, s15, v8
	s_nop 1
	v_addc_co_u32_e32 v9, vcc, 0, v9, vcc
	global_load_dwordx4 v[186:189], v[8:9], off
	v_add_u32_e32 v8, s24, v81
	v_ashrrev_i32_e32 v9, 31, v8
	v_lshlrev_b64 v[8:9], 13, v[8:9]
	v_lshl_add_u64 v[8:9], s[4:5], 0, v[8:9]
	v_lshl_add_u64 v[8:9], v[8:9], 0, s[22:23]
	v_lshl_add_u64 v[8:9], v[8:9], 0, v[70:71]
	v_add_co_u32_e32 v8, vcc, s15, v8
	s_nop 1
	v_addc_co_u32_e32 v9, vcc, 0, v9, vcc
	global_load_dwordx4 v[190:193], v[8:9], off
	v_add_u32_e32 v8, s24, v82
	v_ashrrev_i32_e32 v9, 31, v8
	v_lshlrev_b64 v[8:9], 13, v[8:9]
	v_lshl_add_u64 v[8:9], s[4:5], 0, v[8:9]
	v_lshl_add_u64 v[8:9], v[8:9], 0, s[22:23]
	v_lshl_add_u64 v[8:9], v[8:9], 0, v[70:71]
	v_add_co_u32_e32 v8, vcc, s15, v8
	s_mov_b64 s[22:23], 0x18c84800
	s_nop 0
	v_addc_co_u32_e32 v9, vcc, 0, v9, vcc
	global_load_dwordx4 v[194:197], v[8:9], off
	s_waitcnt vmcnt(14)
	ds_write_b128 v92, v[128:131] offset:61440
	s_waitcnt vmcnt(13)
	ds_write_b128 v93, v[132:135] offset:61440
	s_waitcnt vmcnt(12)
	ds_write_b128 v94, v[136:139] offset:61440
	s_waitcnt vmcnt(11)
	ds_write_b128 v95, v[140:143] offset:61440
	s_waitcnt vmcnt(10)
	ds_write_b128 v96, v[144:147] offset:61440
	s_waitcnt vmcnt(9)
	ds_write_b128 v97, v[148:151] offset:61440
	s_waitcnt vmcnt(8)
	ds_write_b128 v98, v[152:155] offset:61440
	s_waitcnt vmcnt(7)
	ds_write_b128 v99, v[156:159] offset:61440
	s_waitcnt vmcnt(6)
	ds_write_b128 v100, v[160:163]
	s_waitcnt vmcnt(5)
	ds_write_b128 v101, v[164:167]
	s_waitcnt vmcnt(4)
	ds_write_b128 v85, v[178:181] offset:17408
	s_waitcnt vmcnt(3)
	ds_write_b128 v92, v[182:185] offset:26624
	s_waitcnt vmcnt(2)
	ds_write_b128 v93, v[186:189] offset:26624
	s_waitcnt vmcnt(1)
	ds_write_b128 v94, v[190:193] offset:26624
	s_waitcnt vmcnt(0)
	ds_write_b128 v95, v[194:197] offset:26624
	s_waitcnt lgkmcnt(0)
	s_barrier
; #define LAS __attribute__((address_space(3)))
; #define MFMA16(x, y, c) __builtin_amdgcn_mfma_f32_16x16x32_bf16((x), (y), (c), 0, 0, 0)
; __device__ __forceinline__ void gla_passC(LAS unsigned char* lds, int uidx, const bf16_t* PR, const bf16_t* SUB, const bf16_t* QT, const bf16_t* AM, const float* gn  ,
;                                           bf16_t* Y, int tid, int wid, int lane) {
;     ...
;     f32x4 acc[2][4];
; #pragma unroll
;     for (int a = 0; a < 2; ++a)
; #pragma unroll
;         for (int it = 0; it < 4; ++it) acc[a][it] = (f32x4){0.f, 0.f, 0.f, 0.f};
; #pragma unroll
;     for (int ks = 0; ks < 4; ++ks) { bf16x8 x[2];
; #pragma unroll
;         for (int a = 0; a < 2; ++a) x[a] = tr_frag<272>(Sn, 2 * wid + a, ks, lane);
; #pragma unroll
;         for (int it = 0; it < 4; ++it) { const bf16x8 y = *(const LAS bf16x8*)(Qs + (16 * it + r) * 136 + 32 * ks + 8 * q);
; #pragma unroll
;             for (int a = 0; a < 2; ++a) acc[a][it] = MFMA16(x[a], y, acc[a][it]); } }
; #pragma unroll
;     for (int ks = 0; ks < 2; ++ks) { bf16x8 x[2];
; #pragma unroll
;         for (int a = 0; a < 2; ++a) x[a] = tr_frag<272>(Vn, 2 * wid + a, ks, lane);
; #pragma unroll
;         for (int it = 0; it < 4; ++it) { const bf16x8 y = *(const LAS bf16x8*)(As + (16 * it + r) * 72 + 32 * ks + 8 * q);
; #pragma unroll
;             for (int a = 0; a < 2; ++a) acc[a][it] = MFMA16(x[a], y, acc[a][it]); } }
	ds_read_u16 v8, v86 offset:61440
	ds_read_u16 v12, v86 offset:61984
	ds_read_u16 v9, v86 offset:62528
	ds_read_u16 v13, v86 offset:63072
	ds_read_u16 v10, v86 offset:63616
	ds_read_u16 v14, v86 offset:64160
	ds_read_u16 v11, v86 offset:64704
	ds_read_u16 v15, v86 offset:65248
	ds_read_u16 v24, v86 offset:61472
	ds_read_u16 v28, v86 offset:62016
	ds_read_u16 v25, v86 offset:62560
	ds_read_u16 v29, v86 offset:63104
	ds_read_u16 v26, v86 offset:63648
	ds_read_u16 v30, v86 offset:64192
	ds_read_u16 v27, v86 offset:64736
	ds_read_u16 v31, v86 offset:65280
	s_waitcnt lgkmcnt(8)
	v_perm_b32 v11, v15, v11, s13
	v_perm_b32 v10, v14, v10, s13
	v_perm_b32 v9, v13, v9, s13
	v_perm_b32 v8, v12, v8, s13
	ds_read_b128 v[12:15], v102
	s_waitcnt lgkmcnt(1)
	v_perm_b32 v27, v31, v27, s13
	v_perm_b32 v26, v30, v26, s13
	v_perm_b32 v25, v29, v25, s13
	v_perm_b32 v24, v28, v24, s13
	ds_read_b128 v[28:31], v102 offset:4352
	ds_read_b128 v[40:43], v102 offset:8704
	ds_read_b128 v[110:113], v102 offset:13056
	s_waitcnt lgkmcnt(3)
	v_mfma_f32_16x16x32_bf16 v[16:19], v[8:11], v[12:15], 0
	v_mfma_f32_16x16x32_bf16 v[12:15], v[24:27], v[12:15], 0
	s_waitcnt lgkmcnt(2)
	v_mfma_f32_16x16x32_bf16 v[32:35], v[8:11], v[28:31], 0
	v_mfma_f32_16x16x32_bf16 v[28:31], v[24:27], v[28:31], 0
	s_waitcnt lgkmcnt(1)
	v_mfma_f32_16x16x32_bf16 v[44:47], v[8:11], v[40:43], 0
	v_mfma_f32_16x16x32_bf16 v[40:43], v[24:27], v[40:43], 0
	s_waitcnt lgkmcnt(0)
	v_mfma_f32_16x16x32_bf16 v[8:11], v[8:11], v[110:113], 0
	v_mfma_f32_16x16x32_bf16 v[24:27], v[24:27], v[110:113], 0
	ds_read_u16 v71, v103 offset:61984
	ds_read_u16 v72, v103 offset:62528
	ds_read_u16 v73, v103 offset:63072
	ds_read_u16 v76, v103 offset:63616
	ds_read_u16 v77, v103 offset:64160
	ds_read_u16 v109, v103 offset:64704
	ds_read_u16 v110, v103 offset:65248
	ds_read_u16 v114, v103 offset:61440
	ds_read_u16 v118, v103 offset:61472
	ds_read_u16 v122, v103 offset:62016
	ds_read_u16 v119, v103 offset:62560
	ds_read_u16 v123, v103 offset:63104
	ds_read_u16 v120, v103 offset:63648
	ds_read_u16 v124, v103 offset:64192
	ds_read_u16 v121, v103 offset:64736
	ds_read_u16 v125, v103 offset:65280
	s_waitcnt lgkmcnt(9)
	v_perm_b32 v113, v110, v109, s13
	v_perm_b32 v112, v77, v76, s13
	v_perm_b32 v111, v73, v72, s13
	s_waitcnt lgkmcnt(8)
	v_perm_b32 v110, v71, v114, s13
	ds_read_b128 v[114:117], v102 offset:64
	s_waitcnt lgkmcnt(1)
	v_perm_b32 v121, v125, v121, s13
	v_perm_b32 v120, v124, v120, s13
	v_perm_b32 v119, v123, v119, s13
	v_perm_b32 v118, v122, v118, s13
	s_waitcnt lgkmcnt(0)
	v_mfma_f32_16x16x32_bf16 v[16:19], v[110:113], v[114:117], v[16:19]
	v_mfma_f32_16x16x32_bf16 v[12:15], v[118:121], v[114:117], v[12:15]
	ds_read_b128 v[114:117], v102 offset:4416
	s_waitcnt lgkmcnt(0)
	v_mfma_f32_16x16x32_bf16 v[32:35], v[110:113], v[114:117], v[32:35]
	v_mfma_f32_16x16x32_bf16 v[28:31], v[118:121], v[114:117], v[28:31]
	ds_read_b128 v[114:117], v102 offset:8768
	s_waitcnt lgkmcnt(0)
	v_mfma_f32_16x16x32_bf16 v[44:47], v[110:113], v[114:117], v[44:47]
	v_mfma_f32_16x16x32_bf16 v[40:43], v[118:121], v[114:117], v[40:43]
	ds_read_b128 v[114:117], v102 offset:13120
	s_waitcnt lgkmcnt(0)
	v_mfma_f32_16x16x32_bf16 v[8:11], v[110:113], v[114:117], v[8:11]
	v_mfma_f32_16x16x32_bf16 v[24:27], v[118:121], v[114:117], v[24:27]
	ds_read_u16 v71, v87 offset:35360
	ds_read_u16 v72, v87 offset:35904
	ds_read_u16 v73, v87 offset:36448
	ds_read_u16 v76, v87 offset:36992
	ds_read_u16 v77, v87 offset:37536
	ds_read_u16 v109, v87 offset:38080
	ds_read_u16 v110, v87 offset:38624
	ds_read_u16 v114, v87 offset:34816
	ds_read_u16 v118, v87 offset:34848
	ds_read_u16 v122, v87 offset:35392
	ds_read_u16 v119, v87 offset:35936
	ds_read_u16 v123, v87 offset:36480
	ds_read_u16 v120, v87 offset:37024
	ds_read_u16 v124, v87 offset:37568
	ds_read_u16 v121, v87 offset:38112
	ds_read_u16 v125, v87 offset:38656
	s_waitcnt lgkmcnt(9)
	v_perm_b32 v113, v110, v109, s13
	v_perm_b32 v112, v77, v76, s13
	v_perm_b32 v111, v73, v72, s13
	s_waitcnt lgkmcnt(8)
	v_perm_b32 v110, v71, v114, s13
	ds_read_b128 v[114:117], v102 offset:128
	s_waitcnt lgkmcnt(1)
	v_perm_b32 v121, v125, v121, s13
	v_perm_b32 v120, v124, v120, s13
	v_perm_b32 v119, v123, v119, s13
	v_perm_b32 v118, v122, v118, s13
	s_waitcnt lgkmcnt(0)
	v_mfma_f32_16x16x32_bf16 v[16:19], v[110:113], v[114:117], v[16:19]
	v_mfma_f32_16x16x32_bf16 v[12:15], v[118:121], v[114:117], v[12:15]
	ds_read_b128 v[114:117], v102 offset:4480
	s_waitcnt lgkmcnt(0)
	v_mfma_f32_16x16x32_bf16 v[32:35], v[110:113], v[114:117], v[32:35]
	v_mfma_f32_16x16x32_bf16 v[28:31], v[118:121], v[114:117], v[28:31]
	ds_read_b128 v[114:117], v102 offset:8832
	s_waitcnt lgkmcnt(0)
	v_mfma_f32_16x16x32_bf16 v[44:47], v[110:113], v[114:117], v[44:47]
	v_mfma_f32_16x16x32_bf16 v[40:43], v[118:121], v[114:117], v[40:43]
	ds_read_b128 v[114:117], v102 offset:13184
	s_waitcnt lgkmcnt(0)
	v_mfma_f32_16x16x32_bf16 v[8:11], v[110:113], v[114:117], v[8:11]
	v_mfma_f32_16x16x32_bf16 v[24:27], v[118:121], v[114:117], v[24:27]
	ds_read_u16 v71, v87 offset:52224
	ds_read_u16 v72, v87 offset:52768
	ds_read_u16 v73, v87 offset:53312
	ds_read_u16 v76, v87 offset:53856
	ds_read_u16 v77, v87 offset:54400
	ds_read_u16 v109, v87 offset:54944
	ds_read_u16 v110, v87 offset:55488
	ds_read_u16 v111, v87 offset:56032
	ds_read_u16 v118, v87 offset:52256
	ds_read_u16 v122, v87 offset:52800
	ds_read_u16 v119, v87 offset:53344
	ds_read_u16 v123, v87 offset:53888
	ds_read_u16 v120, v87 offset:54432
	ds_read_u16 v124, v87 offset:54976
	ds_read_u16 v121, v87 offset:55520
	ds_read_u16 v125, v87 offset:56064
	s_waitcnt lgkmcnt(8)
; #define LAS __attribute__((address_space(3)))
; #define MFMA16(x, y, c) __builtin_amdgcn_mfma_f32_16x16x32_bf16((x), (y), (c), 0, 0, 0)
; __device__ __forceinline__ void gla_passC(LAS unsigned char* lds, int uidx, const bf16_t* PR, const bf16_t* SUB, const bf16_t* QT, const bf16_t* AM, const float* gn  ,
;                                           bf16_t* Y, int tid, int wid, int lane) {
;     ...
;     for (int ks = 0; ks < 2; ++ks) { bf16x8 x[2];
; #pragma unroll
;         for (int a = 0; a < 2; ++a) x[a] = tr_frag<272>(Vn, 2 * wid + a, ks, lane);
; #pragma unroll
;         for (int it = 0; it < 4; ++it) { const bf16x8 y = *(const LAS bf16x8*)(As + (16 * it + r) * 72 + 32 * ks + 8 * q);
; #pragma unroll
;             for (int a = 0; a < 2; ++a) acc[a][it] = MFMA16(x[a], y, acc[a][it]); } }
;     __syncthreads();
; #pragma unroll
;     for (int a = 0; a < 2; ++a)
; #pragma unroll
;         for (int it = 0; it < 4; ++it) *(LAS f32x4*)(Of + (16 * it + r) * 260 + 32 * wid + 16 * a + 4 * q) = acc[a][it];
;     __syncthreads();
	v_perm_b32 v113, v111, v110, s13
	v_perm_b32 v112, v109, v77, s13
	v_perm_b32 v111, v76, v73, s13
	v_perm_b32 v110, v72, v71, s13
	ds_read_b128 v[114:117], v102 offset:192
	s_waitcnt lgkmcnt(1)
	v_perm_b32 v121, v125, v121, s13
	v_perm_b32 v120, v124, v120, s13
	v_perm_b32 v119, v123, v119, s13
	v_perm_b32 v118, v122, v118, s13
	s_waitcnt lgkmcnt(0)
	v_mfma_f32_16x16x32_bf16 v[16:19], v[110:113], v[114:117], v[16:19]
	v_mfma_f32_16x16x32_bf16 v[12:15], v[118:121], v[114:117], v[12:15]
	ds_read_b128 v[114:117], v102 offset:4544
	s_waitcnt lgkmcnt(0)
	v_mfma_f32_16x16x32_bf16 v[32:35], v[110:113], v[114:117], v[32:35]
	v_mfma_f32_16x16x32_bf16 v[28:31], v[118:121], v[114:117], v[28:31]
	ds_read_b128 v[114:117], v102 offset:8896
	s_waitcnt lgkmcnt(0)
	v_mfma_f32_16x16x32_bf16 v[44:47], v[110:113], v[114:117], v[44:47]
	v_mfma_f32_16x16x32_bf16 v[40:43], v[118:121], v[114:117], v[40:43]
	ds_read_b128 v[114:117], v102 offset:13248
	s_waitcnt lgkmcnt(0)
	v_mfma_f32_16x16x32_bf16 v[8:11], v[110:113], v[114:117], v[8:11]
	v_mfma_f32_16x16x32_bf16 v[24:27], v[118:121], v[114:117], v[24:27]
	ds_read_u16 v71, v86 offset:27168
	ds_read_u16 v72, v86 offset:27712
	ds_read_u16 v73, v86 offset:28256
	ds_read_u16 v76, v86 offset:28800
	ds_read_u16 v77, v86 offset:29344
	ds_read_u16 v109, v86 offset:29888
	ds_read_u16 v110, v86 offset:30432
	ds_read_u16 v114, v86 offset:26624
	ds_read_u16 v118, v86 offset:26656
	ds_read_u16 v122, v86 offset:27200
	ds_read_u16 v119, v86 offset:27744
	ds_read_u16 v123, v86 offset:28288
	ds_read_u16 v120, v86 offset:28832
	ds_read_u16 v124, v86 offset:29376
	ds_read_u16 v121, v86 offset:29920
	ds_read_u16 v125, v86 offset:30464
	s_waitcnt lgkmcnt(9)
	v_perm_b32 v113, v110, v109, s13
	v_perm_b32 v112, v77, v76, s13
	v_perm_b32 v111, v73, v72, s13
	s_waitcnt lgkmcnt(8)
	v_perm_b32 v110, v71, v114, s13
	ds_read_b128 v[114:117], v104 offset:17408
	s_waitcnt lgkmcnt(1)
	v_perm_b32 v121, v125, v121, s13
	v_perm_b32 v120, v124, v120, s13
	v_perm_b32 v119, v123, v119, s13
	v_perm_b32 v118, v122, v118, s13
	s_waitcnt lgkmcnt(0)
	v_mfma_f32_16x16x32_bf16 v[16:19], v[110:113], v[114:117], v[16:19]
	v_mfma_f32_16x16x32_bf16 v[12:15], v[118:121], v[114:117], v[12:15]
	ds_read_b128 v[114:117], v104 offset:19712
	s_waitcnt lgkmcnt(0)
	v_mfma_f32_16x16x32_bf16 v[32:35], v[110:113], v[114:117], v[32:35]
	v_mfma_f32_16x16x32_bf16 v[28:31], v[118:121], v[114:117], v[28:31]
	ds_read_b128 v[114:117], v104 offset:22016
	s_waitcnt lgkmcnt(0)
	v_mfma_f32_16x16x32_bf16 v[44:47], v[110:113], v[114:117], v[44:47]
	v_mfma_f32_16x16x32_bf16 v[40:43], v[118:121], v[114:117], v[40:43]
	ds_read_b128 v[114:117], v104 offset:24320
	s_waitcnt lgkmcnt(0)
	v_mfma_f32_16x16x32_bf16 v[8:11], v[110:113], v[114:117], v[8:11]
	v_mfma_f32_16x16x32_bf16 v[24:27], v[118:121], v[114:117], v[24:27]
	ds_read_u16 v71, v86 offset:44032
	ds_read_u16 v72, v86 offset:44576
	ds_read_u16 v73, v86 offset:45120
	ds_read_u16 v76, v86 offset:45664
	ds_read_u16 v77, v86 offset:46208
	ds_read_u16 v109, v86 offset:46752
	ds_read_u16 v110, v86 offset:47296
	ds_read_u16 v111, v86 offset:47840
	ds_read_u16 v118, v86 offset:44064
	ds_read_u16 v122, v86 offset:44608
	ds_read_u16 v119, v86 offset:45152
	ds_read_u16 v123, v86 offset:45696
	ds_read_u16 v120, v86 offset:46240
	ds_read_u16 v124, v86 offset:46784
	ds_read_u16 v121, v86 offset:47328
	ds_read_u16 v125, v86 offset:47872
	s_waitcnt lgkmcnt(8)
	v_perm_b32 v113, v111, v110, s13
	v_perm_b32 v112, v109, v77, s13
	v_perm_b32 v111, v76, v73, s13
	v_perm_b32 v110, v72, v71, s13
	ds_read_b128 v[114:117], v104 offset:17472
	s_waitcnt lgkmcnt(1)
	v_perm_b32 v121, v125, v121, s13
	v_perm_b32 v120, v124, v120, s13
	v_perm_b32 v119, v123, v119, s13
	v_perm_b32 v118, v122, v118, s13
	s_waitcnt lgkmcnt(0)
	v_mfma_f32_16x16x32_bf16 v[16:19], v[110:113], v[114:117], v[16:19]
	v_mfma_f32_16x16x32_bf16 v[12:15], v[118:121], v[114:117], v[12:15]
	ds_read_b128 v[114:117], v104 offset:19776
	s_waitcnt lgkmcnt(0)
	v_mfma_f32_16x16x32_bf16 v[32:35], v[110:113], v[114:117], v[32:35]
	v_mfma_f32_16x16x32_bf16 v[28:31], v[118:121], v[114:117], v[28:31]
	ds_read_b128 v[114:117], v104 offset:22080
	s_waitcnt lgkmcnt(0)
	v_mfma_f32_16x16x32_bf16 v[44:47], v[110:113], v[114:117], v[44:47]
	v_mfma_f32_16x16x32_bf16 v[40:43], v[118:121], v[114:117], v[40:43]
	ds_read_b128 v[114:117], v104 offset:24384
	s_waitcnt lgkmcnt(0)
	s_barrier
	v_mfma_f32_16x16x32_bf16 v[8:11], v[110:113], v[114:117], v[8:11]
	v_mfma_f32_16x16x32_bf16 v[24:27], v[118:121], v[114:117], v[24:27]
	ds_write_b128 v105, v[16:19] offset:61440
	ds_write_b128 v106, v[32:35] offset:61440
	ds_write_b128 v107, v[44:47] offset:61440
	s_nop 3
	ds_write_b128 v108, v[8:11] offset:61440
	ds_write_b128 v105, v[12:15] offset:61504
	ds_write_b128 v106, v[28:31] offset:61504
	ds_write_b128 v107, v[40:43] offset:61504
	ds_write_b128 v108, v[24:27] offset:61504
	s_waitcnt lgkmcnt(0)
	s_barrier
; #define LAS __attribute__((address_space(3)))
; __device__ __forceinline__ void gla_passC(LAS unsigned char* lds, int uidx, const bf16_t* PR, const bf16_t* SUB, const bf16_t* QT, const bf16_t* AM, const float* gn  ,
;                                           bf16_t* Y, int tid, int wid, int lane) {
;     ...
;     { const int i = tid >> 3, seg = tid & 7; f32x4 o[8]; float ss = 0.f;
; #pragma unroll
;       for (int j = 0; j < 8; ++j) { o[j] = *(const LAS f32x4*)(Of + i * 260 + seg * 32 + 4 * j); ss += (o[j].x * o[j].x + o[j].y * o[j].y) + (o[j].z * o[j].z + o[j].w * o[j].w); }
;       ss += __shfl_xor(ss, 1); ss += __shfl_xor(ss, 2); ss += __shfl_xor(ss, 4);
;       const float rstd = rsqrtf(ss * (1.f / DV) + EPS);
;       const bf16_t* gp = PR + (size_t)(tok0 + i) * PRW + 3072 + h * DV + seg * 32; const float* gnp = gn + h * DV + seg * 32; bf16_t* yp = Y + (size_t)(tok0 + i) * DM + 1024 + h * DV + seg * 32;
; #pragma unroll
;       for (int j = 0; j < 4; ++j) { const u32x4 g = ogr[j]; const f32x4 n0 = *(const f32x4*)(gnp + 8 * j), n1 = *(const f32x4*)(gnp + 8 * j + 4); const f32x4 a0 = o[2 * j], a1 = o[2 * j + 1]; u32x4 w;
	ds_read_b128 v[44:47], v88 offset:61440
	ds_read_b128 v[40:43], v88 offset:61456
	ds_read_b128 v[32:35], v88 offset:61472
	ds_read_b128 v[28:31], v88 offset:61488
	ds_read_b128 v[24:27], v88 offset:61504
	ds_read_b128 v[16:19], v88 offset:61520
	s_waitcnt lgkmcnt(5)
	v_mov_b32_e32 v10, v45
	s_waitcnt lgkmcnt(4)
	v_mov_b32_e32 v11, v41
	v_mov_b32_e32 v8, v44
	v_mov_b32_e32 v9, v40
	v_pk_mul_f32 v[10:11], v[10:11], v[10:11]
	v_mov_b32_e32 v12, v47
	v_mov_b32_e32 v13, v43
	v_pk_fma_f32 v[8:9], v[8:9], v[8:9], v[10:11]
	v_mov_b32_e32 v10, v46
	v_mov_b32_e32 v11, v42
	v_pk_mul_f32 v[12:13], v[12:13], v[12:13]
	v_lshlrev_b32_e32 v118, 16, v36
	v_pk_fma_f32 v[10:11], v[10:11], v[10:11], v[12:13]
	s_waitcnt lgkmcnt(3)
	v_pk_mul_f32 v[12:13], v[32:33], v[32:33]
	v_pk_add_f32 v[8:9], v[8:9], v[10:11]
	v_pk_mul_f32 v[10:11], v[34:35], v[34:35]
	v_pk_add_f32 v[8:9], v[8:9], v[8:9] op_sel:[0,1] op_sel_hi:[1,0]
	v_pk_mov_b32 v[14:15], v[12:13], v[10:11] op_sel:[1,0]
	v_mov_b32_e32 v13, v11
	v_pk_add_f32 v[10:11], v[14:15], v[12:13]
	s_waitcnt lgkmcnt(1)
	v_mul_f32_e32 v12, v24, v24
	v_mul_f32_e32 v13, v25, v25
	v_pk_add_f32 v[10:11], v[10:11], v[10:11] op_sel:[0,1] op_sel_hi:[1,0]
	v_mov_b32_e32 v9, v12
	v_mov_b32_e32 v11, v13
	v_pk_add_f32 v[8:9], v[8:9], v[10:11]
	v_mul_f32_e32 v10, v29, v29
	v_mul_f32_e32 v12, v31, v31
	v_mul_f32_e32 v14, v26, v26
	v_mul_f32_e32 v15, v27, v27
	v_pk_fma_f32 v[10:11], v[28:29], v[28:29], v[10:11] op_sel_hi:[1,1,0]
	v_pk_fma_f32 v[12:13], v[30:31], v[30:31], v[12:13] op_sel_hi:[1,1,0]
	v_mov_b32_e32 v11, v14
	v_mov_b32_e32 v13, v15
	v_pk_add_f32 v[10:11], v[10:11], v[12:13]
	s_nop 0
	v_pk_add_f32 v[72:73], v[8:9], v[10:11]
	s_waitcnt lgkmcnt(0)
	v_pk_mul_f32 v[8:9], v[18:19], v[18:19]
	v_pk_mul_f32 v[10:11], v[16:17], v[16:17]
	v_pk_add_f32 v[72:73], v[72:73], v[72:73] op_sel:[0,1] op_sel_hi:[1,0]
	v_pk_mov_b32 v[12:13], v[10:11], v[8:9] op_sel:[1,0]
	v_mov_b32_e32 v11, v9
	v_pk_add_f32 v[76:77], v[12:13], v[10:11]
	ds_read_b128 v[12:15], v88 offset:61536
	ds_read_b128 v[8:11], v88 offset:61552
	v_pk_add_f32 v[76:77], v[76:77], v[76:77] op_sel:[0,1] op_sel_hi:[1,0]
	s_waitcnt lgkmcnt(0)
	v_mul_f32_e32 v71, v8, v8
	v_mul_f32_e32 v109, v9, v9
	v_mov_b32_e32 v73, v71
	v_mov_b32_e32 v77, v109
	v_pk_add_f32 v[72:73], v[72:73], v[76:77]
	v_mul_f32_e32 v76, v13, v13
	v_mul_f32_e32 v110, v10, v10
	v_pk_fma_f32 v[76:77], v[12:13], v[12:13], v[76:77] op_sel_hi:[1,1,0]
	v_mul_f32_e32 v112, v11, v11
	v_mov_b32_e32 v77, v110
	v_mul_f32_e32 v110, v15, v15
	v_pk_fma_f32 v[110:111], v[14:15], v[14:15], v[110:111] op_sel_hi:[1,1,0]
	s_nop 0
	v_mov_b32_e32 v111, v112
	v_pk_add_f32 v[76:77], v[76:77], v[110:111]
	s_nop 0
	v_pk_add_f32 v[72:73], v[72:73], v[76:77]
	v_lshl_add_u64 v[76:77], v[74:75], 0, v[168:169]
	v_add_f32_e32 v71, v72, v73
	ds_bpermute_b32 v72, v89, v71
	v_lshl_add_u64 v[74:75], v[76:77], 0, s[22:23]
	s_waitcnt lgkmcnt(0)
	v_add_f32_e32 v71, v71, v72
	ds_bpermute_b32 v72, v90, v71
	s_waitcnt lgkmcnt(0)
	v_add_f32_e32 v71, v71, v72
	ds_bpermute_b32 v72, v91, v71
	s_waitcnt lgkmcnt(0)
	v_add_f32_e32 v71, v71, v72
	v_fmamk_f32 v71, v71, 0x3b800000, v212
	v_cmp_gt_f32_e32 vcc, s14, v71
	v_mul_f32_e32 v72, 0x4b800000, v71
	s_nop 0
	v_cndmask_b32_e32 v71, v71, v72, vcc
	v_rsq_f32_e32 v71, v71
	s_nop 0
	v_mul_f32_e32 v72, 0x45800000, v71
	v_cndmask_b32_e32 v71, v71, v72, vcc
	v_lshl_add_u64 v[72:73], v[66:67], 0, s[10:11]
	global_load_dwordx4 v[110:113], v[72:73], off offset:16
	global_load_dwordx4 v[114:117], v[72:73], off
	global_load_dwordx4 v[198:201], v[72:73], off offset:48
	global_load_dwordx4 v[202:205], v[72:73], off offset:32
	global_load_dwordx4 v[206:209], v[72:73], off offset:80
	global_load_dwordx4 v[228:231], v[72:73], off offset:64
	global_load_dwordx4 v[232:235], v[72:73], off offset:112
	global_load_dwordx4 v[236:239], v[72:73], off offset:96
	v_mul_f32_e32 v119, v44, v71
	v_mul_f32_e32 v44, 0xbfb8aa3b, v118
	v_exp_f32_e32 v44, v44
	v_mul_f32_e32 v45, v45, v71
	v_mul_f32_e32 v41, v41, v71
	v_mul_f32_e32 v33, v33, v71
	v_add_f32_e32 v44, 1.0, v44
	v_rcp_f32_e32 v120, v44
	v_and_b32_e32 v44, 0xffff0000, v36
	v_mul_f32_e32 v36, 0xbfb8aa3b, v44
	v_exp_f32_e32 v36, v36
	v_mul_f32_e32 v29, v29, v71
	v_mul_f32_e32 v25, v25, v71
	v_mul_f32_e32 v17, v17, v71
	v_add_f32_e32 v36, 1.0, v36
	v_mul_f32_e32 v13, v13, v71
	v_mul_f32_e32 v9, v9, v71
	s_waitcnt vmcnt(0)
; __device__ __forceinline__ unsigned cvt_pk_bf16(float lo, float hi) { unsigned r; asm volatile("v_cvt_pk_bf16_f32 %0, %1, %2" : "=v"(r) : "v"(lo), "v"(hi)); return r; }
; __device__ __forceinline__ float bf_lo(unsigned w) { return __uint_as_float(w << 16); }
; __device__ __forceinline__ float bf_hi(unsigned w) { return __uint_as_float(w & 0xffff0000u); }
; __device__ __forceinline__ float silu_f(float x) { return x * __builtin_amdgcn_rcpf(1.f + __expf(-x)); }
; __device__ __forceinline__ void gla_passC(LAS unsigned char* lds, int uidx, const bf16_t* PR, const bf16_t* SUB, const bf16_t* QT, const bf16_t* AM, const float* gn  ,
;                                           bf16_t* Y, int tid, int wid, int lane) {
;     ...
;       for (int j = 0; j < 4; ++j) { const u32x4 g = ogr[j]; const f32x4 n0 = *(const f32x4*)(gnp + 8 * j), n1 = *(const f32x4*)(gnp + 8 * j + 4); const f32x4 a0 = o[2 * j], a1 = o[2 * j + 1]; u32x4 w;
;           w.x = cvt_pk_bf16(a0.x * rstd * n0.x * silu_f(bf_lo(g.x)), a0.y * rstd * n0.y * silu_f(bf_hi(g.x)));
;           w.y = cvt_pk_bf16(a0.z * rstd * n0.z * silu_f(bf_lo(g.y)), a0.w * rstd * n0.w * silu_f(bf_hi(g.y)));
;           w.z = cvt_pk_bf16(a1.x * rstd * n1.x * silu_f(bf_lo(g.z)), a1.y * rstd * n1.y * silu_f(bf_hi(g.z)));
;           w.w = cvt_pk_bf16(a1.z * rstd * n1.z * silu_f(bf_lo(g.w)), a1.w * rstd * n1.w * silu_f(bf_hi(g.w)));
;           *(u32x4*)(yp + 8 * j) = w; } }
	v_mov_b32_e32 v121, v114
	v_rcp_f32_e32 v114, v36
	v_pk_mul_f32 v[118:119], v[120:121], v[118:119]
	v_pk_mul_f32 v[44:45], v[114:115], v[44:45]
	s_nop 0
	v_mul_f32_e32 v36, v44, v45
	v_lshlrev_b32_e32 v44, 16, v37
	v_mul_f32_e32 v45, v46, v71
	v_mul_f32_e32 v46, 0xbfb8aa3b, v44
	v_exp_f32_e32 v46, v46
	v_mov_b32_e32 v115, v116
	v_mul_f32_e32 v109, v118, v119
	v_cvt_pk_bf16_f32 v36, v109, v36
	v_add_f32_e32 v46, 1.0, v46
	v_rcp_f32_e32 v114, v46
	s_nop 0
	v_pk_mul_f32 v[44:45], v[114:115], v[44:45]
	s_nop 0
	v_mul_f32_e32 v46, v44, v45
	v_and_b32_e32 v44, 0xffff0000, v37
	v_mul_f32_e32 v37, 0xbfb8aa3b, v44
	v_exp_f32_e32 v37, v37
	v_mul_f32_e32 v45, v47, v71
	v_mov_b32_e32 v47, v110
	v_add_f32_e32 v37, 1.0, v37
	v_rcp_f32_e32 v116, v37
	s_nop 0
	v_pk_mul_f32 v[44:45], v[116:117], v[44:45]
	s_nop 0
	v_mul_f32_e32 v37, v44, v45
	v_lshlrev_b32_e32 v44, 16, v38
	v_mul_f32_e32 v45, v40, v71
	v_mul_f32_e32 v40, 0xbfb8aa3b, v44
	v_exp_f32_e32 v40, v40
	v_cvt_pk_bf16_f32 v37, v46, v37
	s_nop 0
	v_add_f32_e32 v40, 1.0, v40
	v_rcp_f32_e32 v46, v40
	v_and_b32_e32 v40, 0xffff0000, v38
	v_mul_f32_e32 v38, 0xbfb8aa3b, v40
	v_exp_f32_e32 v38, v38
	v_pk_mul_f32 v[44:45], v[46:47], v[44:45]
	v_add_f32_e32 v38, 1.0, v38
	v_rcp_f32_e32 v110, v38
	v_mul_f32_e32 v44, v44, v45
	v_mov_b32_e32 v45, v112
	v_pk_mul_f32 v[40:41], v[110:111], v[40:41]
	s_nop 0
	v_mul_f32_e32 v38, v40, v41
	v_lshlrev_b32_e32 v40, 16, v39
	v_mul_f32_e32 v41, v42, v71
	v_mul_f32_e32 v42, 0xbfb8aa3b, v40
	v_exp_f32_e32 v42, v42
	v_cvt_pk_bf16_f32 v38, v44, v38
	s_nop 0
	v_add_f32_e32 v42, 1.0, v42
	v_rcp_f32_e32 v44, v42
	s_nop 0
	v_pk_mul_f32 v[40:41], v[44:45], v[40:41]
	s_nop 0
	v_mul_f32_e32 v42, v40, v41
	v_and_b32_e32 v40, 0xffff0000, v39
	v_mul_f32_e32 v39, 0xbfb8aa3b, v40
	v_exp_f32_e32 v39, v39
	v_mul_f32_e32 v41, v43, v71
	v_lshlrev_b32_e32 v44, 16, v20
	v_mul_f32_e32 v45, v32, v71
	v_add_f32_e32 v39, 1.0, v39
	v_rcp_f32_e32 v112, v39
	v_mul_f32_e32 v32, 0xbfb8aa3b, v44
	v_exp_f32_e32 v32, v32
	v_pk_mul_f32 v[40:41], v[112:113], v[40:41]
	s_nop 0
	v_mul_f32_e32 v39, v40, v41
	v_add_co_u32_e32 v40, vcc, s7, v76
	v_cvt_pk_bf16_f32 v39, v42, v39
	v_add_f32_e32 v32, 1.0, v32
	s_nop 0
	v_addc_co_u32_e32 v41, vcc, 0, v77, vcc
	global_store_dwordx4 v[40:41], v[36:39], off offset:2048
	s_nop 1
	v_mov_b32_e32 v36, v198
	v_mov_b32_e32 v37, v199
	v_mov_b32_e32 v38, v200
	v_mov_b32_e32 v39, v201
	s_nop 0
	s_nop 1
	v_mov_b32_e32 v40, v202
	v_mov_b32_e32 v41, v203
	v_mov_b32_e32 v42, v204
	v_mov_b32_e32 v43, v205
	v_rcp_f32_e32 v46, v32
	v_and_b32_e32 v32, 0xffff0000, v20
	v_mul_f32_e32 v20, 0xbfb8aa3b, v32
	v_exp_f32_e32 v20, v20
	v_mov_b32_e32 v47, v40
	v_add_f32_e32 v20, 1.0, v20
	v_rcp_f32_e32 v40, v20
	v_pk_mul_f32 v[44:45], v[46:47], v[44:45]
	v_pk_mul_f32 v[32:33], v[40:41], v[32:33]
	s_nop 0
	v_mul_f32_e32 v20, v32, v33
	v_lshlrev_b32_e32 v32, 16, v21
	v_mul_f32_e32 v33, v34, v71
	v_mul_f32_e32 v34, 0xbfb8aa3b, v32
	v_exp_f32_e32 v34, v34
	v_mov_b32_e32 v41, v42
	v_mul_f32_e32 v44, v44, v45
	v_cvt_pk_bf16_f32 v20, v44, v20
	v_add_f32_e32 v34, 1.0, v34
	v_rcp_f32_e32 v40, v34
	s_nop 0
	v_pk_mul_f32 v[32:33], v[40:41], v[32:33]
	s_nop 0
	v_mul_f32_e32 v34, v32, v33
	v_and_b32_e32 v32, 0xffff0000, v21
	v_mul_f32_e32 v21, 0xbfb8aa3b, v32
	v_exp_f32_e32 v21, v21
	v_mul_f32_e32 v33, v35, v71
	v_mov_b32_e32 v35, v36
	v_add_f32_e32 v21, 1.0, v21
	v_rcp_f32_e32 v42, v21
	s_nop 0
	v_pk_mul_f32 v[32:33], v[42:43], v[32:33]
	s_nop 0
	v_mul_f32_e32 v21, v32, v33
	v_lshlrev_b32_e32 v32, 16, v22
	v_mul_f32_e32 v33, v28, v71
	v_mul_f32_e32 v28, 0xbfb8aa3b, v32
	v_exp_f32_e32 v28, v28
	v_cvt_pk_bf16_f32 v21, v34, v21
	s_nop 0
	v_add_f32_e32 v28, 1.0, v28
	v_rcp_f32_e32 v34, v28
	v_and_b32_e32 v28, 0xffff0000, v22
	v_mul_f32_e32 v22, 0xbfb8aa3b, v28
	v_exp_f32_e32 v22, v22
	v_pk_mul_f32 v[32:33], v[34:35], v[32:33]
	v_lshlrev_b32_e32 v34, 16, v4
	v_mul_f32_e32 v32, v32, v33
	v_add_f32_e32 v22, 1.0, v22
	v_rcp_f32_e32 v36, v22
	v_mov_b32_e32 v33, v38
	v_pk_mul_f32 v[28:29], v[36:37], v[28:29]
	s_nop 0
	v_mul_f32_e32 v22, v28, v29
	v_lshlrev_b32_e32 v28, 16, v23
	v_mul_f32_e32 v29, v30, v71
	v_mul_f32_e32 v30, 0xbfb8aa3b, v28
	v_exp_f32_e32 v30, v30
	v_cvt_pk_bf16_f32 v22, v32, v22
	s_nop 0
	v_add_f32_e32 v30, 1.0, v30
	v_rcp_f32_e32 v32, v30
	s_nop 0
	v_pk_mul_f32 v[28:29], v[32:33], v[28:29]
	s_nop 0
	v_mul_f32_e32 v30, v28, v29
	v_and_b32_e32 v28, 0xffff0000, v23
	v_mul_f32_e32 v23, 0xbfb8aa3b, v28
	v_exp_f32_e32 v23, v23
	v_mul_f32_e32 v29, v31, v71
	v_mul_f32_e32 v33, v24, v71
	v_mul_f32_e32 v24, 0xbfb8aa3b, v34
	v_add_f32_e32 v23, 1.0, v23
	v_rcp_f32_e32 v38, v23
	v_exp_f32_e32 v24, v24
	v_pk_mul_f32 v[28:29], v[38:39], v[28:29]
	s_nop 0
	v_mul_f32_e32 v23, v28, v29
	v_cvt_pk_bf16_f32 v23, v30, v23
; __device__ __forceinline__ unsigned cvt_pk_bf16(float lo, float hi) { unsigned r; asm volatile("v_cvt_pk_bf16_f32 %0, %1, %2" : "=v"(r) : "v"(lo), "v"(hi)); return r; }
; __device__ __forceinline__ float bf_lo(unsigned w) { return __uint_as_float(w << 16); }
; __device__ __forceinline__ float bf_hi(unsigned w) { return __uint_as_float(w & 0xffff0000u); }
; __device__ __forceinline__ float silu_f(float x) { return x * __builtin_amdgcn_rcpf(1.f + __expf(-x)); }
; __device__ __forceinline__ void gla_passC(LAS unsigned char* lds, int uidx, const bf16_t* PR, const bf16_t* SUB, const bf16_t* QT, const bf16_t* AM, const float* gn  ,
;                                           bf16_t* Y, int tid, int wid, int lane) {
;     ...
;       for (int j = 0; j < 4; ++j) { const u32x4 g = ogr[j]; const f32x4 n0 = *(const f32x4*)(gnp + 8 * j), n1 = *(const f32x4*)(gnp + 8 * j + 4); const f32x4 a0 = o[2 * j], a1 = o[2 * j + 1]; u32x4 w;
;           w.x = cvt_pk_bf16(a0.x * rstd * n0.x * silu_f(bf_lo(g.x)), a0.y * rstd * n0.y * silu_f(bf_hi(g.x)));
;           w.y = cvt_pk_bf16(a0.z * rstd * n0.z * silu_f(bf_lo(g.y)), a0.w * rstd * n0.w * silu_f(bf_hi(g.y)));
;           w.z = cvt_pk_bf16(a1.x * rstd * n1.x * silu_f(bf_lo(g.z)), a1.y * rstd * n1.y * silu_f(bf_hi(g.z)));
;           w.w = cvt_pk_bf16(a1.z * rstd * n1.z * silu_f(bf_lo(g.w)), a1.w * rstd * n1.w * silu_f(bf_hi(g.w)));
;           *(u32x4*)(yp + 8 * j) = w; } }
;     __syncthreads();
	global_store_dwordx4 v[74:75], v[20:23], off offset:16
	s_nop 1
	v_mov_b32_e32 v20, v206
	v_mov_b32_e32 v21, v207
	v_mov_b32_e32 v22, v208
	v_mov_b32_e32 v23, v209
	s_nop 0
	s_nop 1
	v_mov_b32_e32 v28, v228
	v_mov_b32_e32 v29, v229
	v_mov_b32_e32 v30, v230
	v_mov_b32_e32 v31, v231
	v_add_f32_e32 v24, 1.0, v24
	v_rcp_f32_e32 v32, v24
	v_mov_b32_e32 v35, v28
	v_and_b32_e32 v28, 0xffff0000, v4
	v_mul_f32_e32 v4, 0xbfb8aa3b, v28
	v_exp_f32_e32 v4, v4
	v_pk_mul_f32 v[32:33], v[32:33], v[34:35]
	v_add_f32_e32 v4, 1.0, v4
	v_rcp_f32_e32 v24, v4
	v_mul_f32_e32 v32, v32, v33
	v_pk_mul_f32 v[24:25], v[24:25], v[28:29]
	v_lshlrev_b32_e32 v28, 16, v5
	v_mul_f32_e32 v4, v24, v25
	v_mul_f32_e32 v24, 0xbfb8aa3b, v28
	v_exp_f32_e32 v24, v24
	v_mov_b32_e32 v29, v30
	v_and_b32_e32 v30, 0xffff0000, v5
	v_mul_f32_e32 v5, 0xbfb8aa3b, v30
	v_add_f32_e32 v24, 1.0, v24
	v_rcp_f32_e32 v24, v24
	v_exp_f32_e32 v5, v5
	v_mul_f32_e32 v25, v26, v71
	v_cvt_pk_bf16_f32 v4, v32, v4
	v_pk_mul_f32 v[24:25], v[24:25], v[28:29]
	v_add_f32_e32 v5, 1.0, v5
	v_mul_f32_e32 v26, v24, v25
	v_rcp_f32_e32 v24, v5
	v_mul_f32_e32 v25, v27, v71
	v_mov_b32_e32 v27, v20
	v_and_b32_e32 v20, 0xffff0000, v6
	v_pk_mul_f32 v[24:25], v[24:25], v[30:31]
	s_nop 0
	v_mul_f32_e32 v5, v24, v25
	v_cvt_pk_bf16_f32 v5, v26, v5
	v_lshlrev_b32_e32 v26, 16, v6
	v_mul_f32_e32 v25, v16, v71
	v_mul_f32_e32 v16, 0xbfb8aa3b, v26
	v_mul_f32_e32 v6, 0xbfb8aa3b, v20
	v_exp_f32_e32 v16, v16
	v_exp_f32_e32 v6, v6
	v_add_f32_e32 v16, 1.0, v16
	v_add_f32_e32 v6, 1.0, v6
	v_rcp_f32_e32 v24, v16
	v_rcp_f32_e32 v16, v6
	v_pk_mul_f32 v[24:25], v[24:25], v[26:27]
	v_pk_mul_f32 v[16:17], v[16:17], v[20:21]
	v_lshlrev_b32_e32 v20, 16, v7
	v_mul_f32_e32 v6, v16, v17
	v_mul_f32_e32 v16, 0xbfb8aa3b, v20
	v_exp_f32_e32 v16, v16
	v_mov_b32_e32 v21, v22
	v_and_b32_e32 v22, 0xffff0000, v7
	v_mul_f32_e32 v7, 0xbfb8aa3b, v22
	v_add_f32_e32 v16, 1.0, v16
	v_rcp_f32_e32 v16, v16
	v_exp_f32_e32 v7, v7
	v_mul_f32_e32 v17, v18, v71
	v_mul_f32_e32 v24, v24, v25
	v_pk_mul_f32 v[16:17], v[16:17], v[20:21]
	v_add_f32_e32 v7, 1.0, v7
	v_mul_f32_e32 v18, v16, v17
	v_rcp_f32_e32 v16, v7
	v_mul_f32_e32 v17, v19, v71
	v_cvt_pk_bf16_f32 v6, v24, v6
	v_mul_f32_e32 v21, v12, v71
	v_pk_mul_f32 v[16:17], v[16:17], v[22:23]
	v_lshlrev_b32_e32 v22, 16, v0
	v_mul_f32_e32 v7, v16, v17
	v_cvt_pk_bf16_f32 v7, v18, v7
	global_store_dwordx4 v[74:75], v[4:7], off offset:32
	s_nop 1
	v_mov_b32_e32 v4, v232
	v_mov_b32_e32 v5, v233
	v_mov_b32_e32 v6, v234
	v_mov_b32_e32 v7, v235
	s_nop 0
	s_nop 1
	v_mov_b32_e32 v16, v236
	v_mov_b32_e32 v17, v237
	v_mov_b32_e32 v18, v238
	v_mov_b32_e32 v19, v239
	v_mul_f32_e32 v12, 0xbfb8aa3b, v22
	v_exp_f32_e32 v12, v12
	v_mov_b32_e32 v23, v16
	v_and_b32_e32 v16, 0xffff0000, v0
	v_mul_f32_e32 v0, 0xbfb8aa3b, v16
	v_exp_f32_e32 v0, v0
	v_add_f32_e32 v12, 1.0, v12
	v_rcp_f32_e32 v20, v12
	v_add_f32_e32 v0, 1.0, v0
	v_rcp_f32_e32 v12, v0
	v_pk_mul_f32 v[20:21], v[20:21], v[22:23]
	v_pk_mul_f32 v[12:13], v[12:13], v[16:17]
	v_lshlrev_b32_e32 v16, 16, v1
	v_mul_f32_e32 v0, v12, v13
	v_mul_f32_e32 v12, 0xbfb8aa3b, v16
	v_exp_f32_e32 v12, v12
	v_mov_b32_e32 v17, v18
	v_and_b32_e32 v18, 0xffff0000, v1
	v_mul_f32_e32 v1, 0xbfb8aa3b, v18
	v_add_f32_e32 v12, 1.0, v12
	v_rcp_f32_e32 v12, v12
	v_exp_f32_e32 v1, v1
	v_mul_f32_e32 v13, v14, v71
	v_mul_f32_e32 v20, v20, v21
	v_pk_mul_f32 v[12:13], v[12:13], v[16:17]
	v_add_f32_e32 v1, 1.0, v1
	v_mul_f32_e32 v14, v12, v13
	v_rcp_f32_e32 v12, v1
	v_mul_f32_e32 v13, v15, v71
	v_cvt_pk_bf16_f32 v0, v20, v0
	v_mov_b32_e32 v15, v4
	v_pk_mul_f32 v[12:13], v[12:13], v[18:19]
	v_and_b32_e32 v4, 0xffff0000, v2
	v_mul_f32_e32 v1, v12, v13
	v_cvt_pk_bf16_f32 v1, v14, v1
	v_lshlrev_b32_e32 v14, 16, v2
	v_mul_f32_e32 v13, v8, v71
	v_mul_f32_e32 v8, 0xbfb8aa3b, v14
	v_mul_f32_e32 v2, 0xbfb8aa3b, v4
	v_exp_f32_e32 v8, v8
	v_exp_f32_e32 v2, v2
	v_add_f32_e32 v8, 1.0, v8
	v_add_f32_e32 v2, 1.0, v2
	v_rcp_f32_e32 v12, v8
	v_rcp_f32_e32 v8, v2
	v_pk_mul_f32 v[12:13], v[12:13], v[14:15]
	v_pk_mul_f32 v[4:5], v[8:9], v[4:5]
	v_lshlrev_b32_e32 v8, 16, v3
	v_mul_f32_e32 v2, v4, v5
	v_mul_f32_e32 v4, 0xbfb8aa3b, v8
	v_exp_f32_e32 v4, v4
	v_mov_b32_e32 v9, v6
	v_and_b32_e32 v6, 0xffff0000, v3
	v_mul_f32_e32 v3, 0xbfb8aa3b, v6
	v_add_f32_e32 v4, 1.0, v4
	v_rcp_f32_e32 v4, v4
	v_exp_f32_e32 v3, v3
	v_mul_f32_e32 v5, v10, v71
	v_mul_f32_e32 v12, v12, v13
	v_pk_mul_f32 v[4:5], v[4:5], v[8:9]
	v_add_f32_e32 v3, 1.0, v3
	v_mul_f32_e32 v8, v4, v5
	v_rcp_f32_e32 v4, v3
	v_mul_f32_e32 v5, v11, v71
	v_cvt_pk_bf16_f32 v2, v12, v2
	v_pk_mul_f32 v[4:5], v[4:5], v[6:7]
	s_nop 0
	v_mul_f32_e32 v3, v4, v5
	v_cvt_pk_bf16_f32 v3, v8, v3
	global_store_dwordx4 v[74:75], v[0:3], off offset:48
	s_barrier
	s_cbranch_scc0 .LBB0_487
